# in-projection GEMM no longer computes the V columns of PX that nothing reads (attention takes V from the transposed GVT output); GVT tiles moved to workgroups 152..219: at most 2 tiles per workgroup i
# speedup vs baseline: 1.5010x; 1.0335x over previous
.LBB0_210:
	v_readlane_b32 s30, v245, 45
	v_readlane_b32 s20, v245, 43
	s_movk_i32 s12, 0x400
	s_mov_b32 s16, 6
	s_movk_i32 s0, 0x4400
	v_readlane_b32 s31, v245, 46
	v_readlane_b32 s21, v245, 44
	s_branch .LBB0_212

.LBB0_212:
	s_lshr_b32 s25, s0, 8
	s_mul_i32 s86, s25, s16
	s_cmp_eq_u32 s24, 1
	s_cselect_b32 s100, 0x98, 0
	s_sub_i32 s100, s69, s100
	s_cmp_lt_u32 s100, s86
	s_cselect_b64 s[0:1], -1, 0
	s_cmp_ge_u32 s100, s86
	v_readfirstlane_b32 s17, v186
	s_cbranch_scc1 .LBB0_218
	s_lshr_b32 s13, s86, 3
	s_and_b32 s18, s86, 7
	s_add_i32 s7, s13, 1
	s_cmp_ge_i32 s67, s18
	s_mov_b64 s[14:15], -1
	s_cbranch_scc0 .LBB0_215
	s_sub_i32 s14, s67, s18
	s_mul_i32 s6, s7, s18
	s_mul_i32 s13, s14, s13
	s_add_i32 s6, s13, s6
	s_mov_b64 s[14:15], 0

.LBB0_217:
	s_lshl_b32 s7, s16, 3
	v_cvt_f32_u32_e32 v0, s7
	s_sub_i32 s15, 0, s7
	v_readlane_b32 s10, v247, 45
	s_add_i32 s6, s6, s10
	s_cmp_eq_u32 s24, 1
	s_cselect_b32 s101, 19, 0
	s_sub_i32 s6, s6, s101
	v_rcp_iflag_f32_e32 v0, v0
	s_abs_i32 s14, s6
	s_ashr_i32 s13, s6, 31
	v_mul_f32_e32 v0, 0x4f7ffffe, v0
	v_cvt_u32_f32_e32 v0, v0
	s_nop 0
	v_readfirstlane_b32 s18, v0
	s_mul_i32 s15, s15, s18
	s_mul_hi_u32 s15, s18, s15
	s_add_i32 s18, s18, s15
	s_mul_hi_u32 s15, s14, s18
	s_mul_i32 s18, s15, s7
	s_sub_i32 s14, s14, s18
	s_add_i32 s19, s15, 1
	s_sub_i32 s18, s14, s7
	s_cmp_ge_u32 s14, s7
	s_cselect_b32 s15, s19, s15
	s_cselect_b32 s14, s18, s14
	s_add_i32 s18, s15, 1
	s_cmp_ge_u32 s14, s7
	s_cselect_b32 s14, s18, s15
	s_xor_b32 s14, s14, s13
	s_sub_i32 s13, s14, s13
	s_lshl_b32 s14, s13, 3
	s_sub_i32 s15, s25, s14
	s_min_i32 s15, s15, 8
	s_abs_i32 s18, s15
	v_cvt_f32_u32_e32 v0, s18
	s_sub_i32 s19, 0, s18
	s_mul_i32 s13, s13, s7
	s_sub_i32 s6, s6, s13
	v_rcp_iflag_f32_e32 v0, v0
	s_abs_i32 s7, s6
	s_xor_b32 s13, s6, s15
	s_ashr_i32 s13, s13, 31
	v_mul_f32_e32 v0, 0x4f7ffffe, v0
	v_cvt_u32_f32_e32 v0, v0
	s_nop 0
	v_readfirstlane_b32 s22, v0
	s_mul_i32 s19, s19, s22
	s_mul_hi_u32 s19, s22, s19
	s_add_i32 s22, s22, s19
	s_mul_hi_u32 s19, s7, s22
	s_mul_i32 s22, s19, s18
	s_sub_i32 s7, s7, s22
	s_add_i32 s23, s19, 1
	s_sub_i32 s22, s7, s18
	s_cmp_ge_u32 s7, s18
	s_cselect_b32 s19, s23, s19
	s_cselect_b32 s7, s22, s7
	s_add_i32 s22, s19, 1
	s_cmp_ge_u32 s7, s18
	s_cselect_b32 s7, s22, s19
	s_xor_b32 s7, s7, s13
	s_sub_i32 s38, s7, s13
	s_mul_i32 s7, s38, s15
	s_sub_i32 s6, s6, s7
	s_add_i32 s13, s6, s14
.LBB0_218:
	s_cmp_eq_u32 s24, 0
	s_cbranch_scc0 .Lvsk_a
	s_cmp_eq_u32 s38, 5
	s_cselect_b32 s38, 6, s38

.LBB0_230:
	s_cmp_eq_u32 s24, 0
	s_cbranch_scc0 .Lvsk_b
	s_cmp_eq_u32 s81, 5
	s_cselect_b32 s81, 6, s81
